# P8 stagger variant: two groups, ~15us delay
# speedup vs baseline: 1.0035x; 1.0035x over previous
.LBB0_1462:
	s_or_b64 exec, exec, s[0:1]
	s_add_u32 s8, s64, 0xac40000
	v_mov_b32_e32 v12, v162
	s_waitcnt lgkmcnt(0)
	s_barrier
	s_cselect_b32 s101, 1, 0
	s_bitcmp1_b32 s2, 3
	s_cbranch_scc0 .Lp8_nodelay
	s_sleep 127
	s_sleep 127
	s_sleep 127
